# SwiGLU epilogue P1/P8: row-group store addresses by constant add from group 0 (no per-group 64-bit mad), stacked on v71
# baseline (speedup 1.0000x reference)
.LBB0_208:
	s_add_u32 s4, s46, 0xfffffe00
	s_addc_u32 s5, s47, -1
	s_add_i32 s2, s76, s3
	v_lshl_add_u32 v140, v141, 4, s2
	ds_read_b128 v[152:155], v140
	ds_read_b128 v[156:159], v140 offset:256
	ds_read_b128 v[160:163], v140 offset:512
	ds_read_b128 v[164:167], v140 offset:768
	s_waitcnt lgkmcnt(0)
	s_waitcnt lgkmcnt(0)
	v_mov_b32_e32 v168, v153
	v_mov_b32_e32 v169, v154
	v_mov_b32_e32 v153, v155
	v_pk_add_f32 v[152:153], v[168:169], v[152:153]
	s_lshl_b32 s2, s10, 8
	v_add_f32_e32 v149, v152, v153
	v_mov_b32_e32 v152, v157
	v_mov_b32_e32 v153, v158
	v_mov_b32_e32 v157, v159
	v_fmamk_f32 v149, v149, 0x3a800000, v148
	v_pk_add_f32 v[152:153], v[152:153], v[156:157]
	v_rsq_f32_e32 v170, v149
	v_add_f32_e32 v149, v152, v153
	v_mov_b32_e32 v152, v161
	v_mov_b32_e32 v153, v162
	v_mov_b32_e32 v161, v163
	v_fmamk_f32 v149, v149, 0x3a800000, v148
	v_pk_add_f32 v[152:153], v[152:153], v[160:161]
	v_rsq_f32_e32 v171, v149
	v_add_f32_e32 v149, v152, v153
	v_mov_b32_e32 v152, v165
	v_mov_b32_e32 v153, v166
	v_mov_b32_e32 v165, v167
	v_fmamk_f32 v149, v149, 0x3a800000, v148
	v_pk_add_f32 v[152:153], v[152:153], v[164:165]
	v_rsq_f32_e32 v172, v149
	v_add_f32_e32 v149, v152, v153
	ds_read_b128 v[152:155], v140 offset:2048
	ds_read_b128 v[156:159], v140 offset:2304
	ds_read_b128 v[160:163], v140 offset:2560
	ds_read_b128 v[164:167], v140 offset:2816
	v_fmamk_f32 v149, v149, 0x3a800000, v148
	s_waitcnt lgkmcnt(0)
	v_mov_b32_e32 v168, v153
	v_mov_b32_e32 v169, v154
	v_mov_b32_e32 v153, v155
	v_pk_add_f32 v[152:153], v[168:169], v[152:153]
	v_rsq_f32_e32 v173, v149
	v_add_f32_e32 v140, v152, v153
	v_mov_b32_e32 v152, v157
	v_mov_b32_e32 v153, v158
	v_mov_b32_e32 v157, v159
	v_fmamk_f32 v140, v140, 0x3a800000, v148
	v_pk_add_f32 v[152:153], v[152:153], v[156:157]
	v_rsq_f32_e32 v168, v140
	v_add_f32_e32 v140, v152, v153
	v_mov_b32_e32 v152, v161
	v_mov_b32_e32 v153, v162
	v_mov_b32_e32 v161, v163
	v_fmamk_f32 v140, v140, 0x3a800000, v148
	v_pk_add_f32 v[152:153], v[152:153], v[160:161]
	v_rsq_f32_e32 v169, v140
	v_add_f32_e32 v140, v152, v153
	v_mov_b32_e32 v152, v165
	v_mov_b32_e32 v153, v166
	v_mov_b32_e32 v165, v167
	v_fmamk_f32 v140, v140, 0x3a800000, v148
	v_pk_add_f32 v[152:153], v[152:153], v[164:165]
	v_rsq_f32_e32 v149, v140
	v_add_f32_e32 v140, v152, v153
	s_add_i32 s2, s2, s59
	v_mul_f32_e32 v153, 0xbfb8aa3b, v170
	v_pk_mul_f32 v[154:155], v[118:119], v[152:153] op_sel:[0,1]
	v_pk_mul_f32 v[156:157], v[114:115], v[152:153] op_sel:[0,1]
	v_pk_mul_f32 v[158:159], v[120:121], v[152:153] op_sel:[0,1]
	v_pk_mul_f32 v[160:161], v[116:117], v[152:153] op_sel:[0,1]
	v_exp_f32_e32 v154, v154
	v_exp_f32_e32 v155, v155
	v_exp_f32_e32 v156, v156
	v_exp_f32_e32 v157, v157
	v_exp_f32_e32 v158, v158
	v_exp_f32_e32 v159, v159
	v_exp_f32_e32 v160, v160
	v_exp_f32_e32 v161, v161
	v_pk_add_f32 v[154:155], v[154:155], 1.0 op_sel_hi:[1,0]
	v_pk_add_f32 v[156:157], v[156:157], 1.0 op_sel_hi:[1,0]
	v_pk_add_f32 v[158:159], v[158:159], 1.0 op_sel_hi:[1,0]
	v_pk_add_f32 v[160:161], v[160:161], 1.0 op_sel_hi:[1,0]
	v_rcp_f32_e32 v154, v154
	v_rcp_f32_e32 v155, v155
	v_rcp_f32_e32 v156, v156
	v_rcp_f32_e32 v157, v157
	v_rcp_f32_e32 v158, v158
	v_rcp_f32_e32 v159, v159
	v_rcp_f32_e32 v160, v160
	v_rcp_f32_e32 v161, v161
	s_nop 0
	v_add_u32_e32 v141, s2, v141
	s_lshl_b32 s2, s60, 7
	s_or_b32 s2, s2, s61
	v_mul_f32_e32 v152, v170, v170
	v_lshl_add_u32 v150, v150, 3, s2
	v_pk_mul_f32 v[120:121], v[120:121], v[128:129]
	v_pk_mul_f32 v[118:119], v[118:119], v[126:127]
	v_pk_mul_f32 v[126:127], v[152:153], v[154:155] op_sel_hi:[0,1]
	v_pk_mul_f32 v[128:129], v[152:153], v[158:159] op_sel_hi:[0,1]
	v_pk_mul_f32 v[114:115], v[114:115], v[122:123]
	v_pk_mul_f32 v[122:123], v[152:153], v[156:157] op_sel_hi:[0,1]
	v_readlane_b32 s2, v255, 0
	v_pk_mul_f32 v[120:121], v[120:121], v[128:129]
	v_pk_mul_f32 v[118:119], v[118:119], v[126:127]
	v_pk_mul_f32 v[116:117], v[116:117], v[124:125]
	v_pk_mul_f32 v[124:125], v[152:153], v[160:161] op_sel_hi:[0,1]
	v_pk_mul_f32 v[114:115], v[114:115], v[122:123]
	v_readlane_b32 s3, v255, 1
	s_waitcnt lgkmcnt(0)
	v_ashrrev_i32_e32 v151, 31, v150
	v_pk_mul_f32 v[116:117], v[116:117], v[124:125]
	v_cvt_pk_bf16_f32 v118, v118, v119
	v_cvt_pk_bf16_f32 v119, v120, v121
	v_cvt_pk_bf16_f32 v120, v114, v115
	v_mov_b64_e32 v[114:115], s[2:3]
	v_cvt_pk_bf16_f32 v121, v116, v117
	v_mad_i64_i32 v[122:123], s[2:3], v141, s50, v[114:115]
	v_lshlrev_b64 v[116:117], 1, v[150:151]
	v_lshl_add_u64 v[116:117], v[122:123], 0, v[116:117]
	s_cmp_eq_u32 s98, 1
	s_cbranch_scc1 .Lwt_0
	global_store_dwordx4 v[116:117], v[118:121], off
	s_branch .Lwtd_0
.Lwt_0:
	global_store_dwordx4 v[116:117], v[118:121], off sc1
.Lwtd_0:
	v_fmamk_f32 v140, v140, 0x3a800000, v148
	v_rsq_f32_e32 v140, v140
	v_mul_f32_e32 v120, 0xbfb8aa3b, v171
	v_pk_mul_f32 v[122:123], v[98:99], v[120:121] op_sel_hi:[1,0]
	v_pk_mul_f32 v[124:125], v[104:105], v[120:121] op_sel_hi:[1,0]
	v_pk_mul_f32 v[126:127], v[100:101], v[120:121] op_sel_hi:[1,0]
	v_pk_mul_f32 v[120:121], v[102:103], v[120:121] op_sel_hi:[1,0]
	v_exp_f32_e32 v122, v122
	v_exp_f32_e32 v123, v123
	v_exp_f32_e32 v124, v124
	v_exp_f32_e32 v125, v125
	v_exp_f32_e32 v126, v126
	v_exp_f32_e32 v127, v127
	v_exp_f32_e32 v120, v120
	v_exp_f32_e32 v121, v121
	v_pk_add_f32 v[122:123], v[122:123], 1.0 op_sel_hi:[1,0]
	v_pk_add_f32 v[124:125], v[124:125], 1.0 op_sel_hi:[1,0]
	v_pk_add_f32 v[126:127], v[126:127], 1.0 op_sel_hi:[1,0]
	v_pk_add_f32 v[120:121], v[120:121], 1.0 op_sel_hi:[1,0]
	v_rcp_f32_e32 v122, v122
	v_rcp_f32_e32 v123, v123
	v_rcp_f32_e32 v124, v124
	v_rcp_f32_e32 v125, v125
	v_rcp_f32_e32 v126, v126
	v_rcp_f32_e32 v127, v127
	v_rcp_f32_e32 v120, v120
	v_rcp_f32_e32 v121, v121
	s_nop 0
	v_mul_f32_e32 v118, v171, v171
	v_pk_mul_f32 v[102:103], v[102:103], v[110:111]
	v_pk_mul_f32 v[110:111], v[118:119], v[120:121] op_sel_hi:[0,1]
	v_pk_mul_f32 v[102:103], v[102:103], v[110:111]
	v_pk_mul_f32 v[100:101], v[100:101], v[108:109]
	v_pk_mul_f32 v[98:99], v[98:99], v[106:107]
	v_pk_mul_f32 v[106:107], v[118:119], v[122:123] op_sel_hi:[0,1]
	v_pk_mul_f32 v[108:109], v[118:119], v[126:127] op_sel_hi:[0,1]
	v_pk_mul_f32 v[104:105], v[104:105], v[112:113]
	v_pk_mul_f32 v[112:113], v[118:119], v[124:125] op_sel_hi:[0,1]
	v_pk_mul_f32 v[108:109], v[100:101], v[108:109]
	v_pk_mul_f32 v[100:101], v[98:99], v[106:107]
	v_cvt_pk_bf16_f32 v98, v102, v103
	s_mov_b64 s[2:3], 0x16000
	v_pk_mul_f32 v[104:105], v[104:105], v[112:113]
	v_lshl_add_u64 v[102:103], v[116:117], 0, s[2:3]
	v_cvt_pk_bf16_f32 v99, v104, v105
	v_cvt_pk_bf16_f32 v100, v100, v101
	v_cvt_pk_bf16_f32 v101, v108, v109
	s_cmp_eq_u32 s98, 1
	s_cbranch_scc1 .Lwt_1
	global_store_dwordx4 v[102:103], v[98:101], off
	s_branch .Lwtd_1

.Lwtd_1:
	s_andn2_b64 vcc, exec, s[0:1]
	s_nop 0
	v_mul_f32_e32 v100, 0xbfb8aa3b, v172
	v_pk_mul_f32 v[102:103], v[82:83], v[100:101] op_sel_hi:[1,0]
	v_pk_mul_f32 v[104:105], v[88:89], v[100:101] op_sel_hi:[1,0]
	v_pk_mul_f32 v[106:107], v[84:85], v[100:101] op_sel_hi:[1,0]
	v_pk_mul_f32 v[100:101], v[86:87], v[100:101] op_sel_hi:[1,0]
	v_exp_f32_e32 v102, v102
	v_exp_f32_e32 v103, v103
	v_exp_f32_e32 v104, v104
	v_exp_f32_e32 v105, v105
	v_exp_f32_e32 v106, v106
	v_exp_f32_e32 v107, v107
	v_exp_f32_e32 v100, v100
	v_exp_f32_e32 v101, v101
	v_pk_add_f32 v[102:103], v[102:103], 1.0 op_sel_hi:[1,0]
	v_pk_add_f32 v[104:105], v[104:105], 1.0 op_sel_hi:[1,0]
	v_pk_add_f32 v[106:107], v[106:107], 1.0 op_sel_hi:[1,0]
	v_pk_add_f32 v[100:101], v[100:101], 1.0 op_sel_hi:[1,0]
	v_rcp_f32_e32 v102, v102
	v_rcp_f32_e32 v103, v103
	v_rcp_f32_e32 v104, v104
	v_rcp_f32_e32 v105, v105
	v_rcp_f32_e32 v106, v106
	v_rcp_f32_e32 v107, v107
	v_rcp_f32_e32 v100, v100
	v_rcp_f32_e32 v101, v101
	s_nop 0
	v_mul_f32_e32 v98, v172, v172
	v_pk_mul_f32 v[86:87], v[86:87], v[94:95]
	v_pk_mul_f32 v[94:95], v[98:99], v[100:101] op_sel_hi:[0,1]
	v_pk_mul_f32 v[86:87], v[86:87], v[94:95]
	v_pk_mul_f32 v[84:85], v[84:85], v[92:93]
	v_pk_mul_f32 v[82:83], v[82:83], v[90:91]
	v_pk_mul_f32 v[90:91], v[98:99], v[102:103] op_sel_hi:[0,1]
	v_pk_mul_f32 v[92:93], v[98:99], v[106:107] op_sel_hi:[0,1]
	v_pk_mul_f32 v[88:89], v[88:89], v[96:97]
	v_pk_mul_f32 v[96:97], v[98:99], v[104:105] op_sel_hi:[0,1]
	v_pk_mul_f32 v[92:93], v[84:85], v[92:93]
	v_pk_mul_f32 v[84:85], v[82:83], v[90:91]
	v_cvt_pk_bf16_f32 v82, v86, v87
	s_mov_b64 s[2:3], 0x2c000
	v_pk_mul_f32 v[88:89], v[88:89], v[96:97]
	v_lshl_add_u64 v[86:87], v[116:117], 0, s[2:3]
	v_cvt_pk_bf16_f32 v83, v88, v89
	v_cvt_pk_bf16_f32 v84, v84, v85
	v_cvt_pk_bf16_f32 v85, v92, v93
	s_cmp_eq_u32 s98, 1
	s_cbranch_scc1 .Lwt_2
	global_store_dwordx4 v[86:87], v[82:85], off
	s_branch .Lwtd_2

.Lwtd_2:
	s_nop 1
	v_mul_f32_e32 v84, 0xbfb8aa3b, v173
	v_pk_mul_f32 v[86:87], v[62:63], v[84:85] op_sel_hi:[1,0]
	v_pk_mul_f32 v[88:89], v[72:73], v[84:85] op_sel_hi:[1,0]
	v_pk_mul_f32 v[90:91], v[64:65], v[84:85] op_sel_hi:[1,0]
	v_pk_mul_f32 v[84:85], v[70:71], v[84:85] op_sel_hi:[1,0]
	v_exp_f32_e32 v86, v86
	v_exp_f32_e32 v87, v87
	v_exp_f32_e32 v88, v88
	v_exp_f32_e32 v89, v89
	v_exp_f32_e32 v90, v90
	v_exp_f32_e32 v91, v91
	v_exp_f32_e32 v84, v84
	v_exp_f32_e32 v85, v85
	v_pk_add_f32 v[86:87], v[86:87], 1.0 op_sel_hi:[1,0]
	v_pk_add_f32 v[88:89], v[88:89], 1.0 op_sel_hi:[1,0]
	v_pk_add_f32 v[90:91], v[90:91], 1.0 op_sel_hi:[1,0]
	v_pk_add_f32 v[84:85], v[84:85], 1.0 op_sel_hi:[1,0]
	v_rcp_f32_e32 v86, v86
	v_rcp_f32_e32 v87, v87
	v_rcp_f32_e32 v88, v88
	v_rcp_f32_e32 v89, v89
	v_rcp_f32_e32 v90, v90
	v_rcp_f32_e32 v91, v91
	v_rcp_f32_e32 v84, v84
	v_rcp_f32_e32 v85, v85
	s_nop 0
	v_mul_f32_e32 v82, v173, v173
	v_pk_mul_f32 v[70:71], v[70:71], v[78:79]
	v_pk_mul_f32 v[78:79], v[82:83], v[84:85] op_sel_hi:[0,1]
	v_pk_mul_f32 v[70:71], v[70:71], v[78:79]
	v_pk_mul_f32 v[64:65], v[64:65], v[76:77]
	v_pk_mul_f32 v[62:63], v[62:63], v[74:75]
	v_pk_mul_f32 v[74:75], v[82:83], v[86:87] op_sel_hi:[0,1]
	v_pk_mul_f32 v[76:77], v[82:83], v[90:91] op_sel_hi:[0,1]
	v_pk_mul_f32 v[72:73], v[72:73], v[80:81]
	v_pk_mul_f32 v[80:81], v[82:83], v[88:89] op_sel_hi:[0,1]
	v_pk_mul_f32 v[76:77], v[64:65], v[76:77]
	v_pk_mul_f32 v[64:65], v[62:63], v[74:75]
	v_cvt_pk_bf16_f32 v62, v70, v71
	s_mov_b64 s[2:3], 0x42000
	v_pk_mul_f32 v[72:73], v[72:73], v[80:81]
	v_lshl_add_u64 v[70:71], v[116:117], 0, s[2:3]
	v_cvt_pk_bf16_f32 v63, v72, v73
	v_cvt_pk_bf16_f32 v64, v64, v65
	v_cvt_pk_bf16_f32 v65, v76, v77
	s_cmp_eq_u32 s98, 1
	s_cbranch_scc1 .Lwt_3
	global_store_dwordx4 v[70:71], v[62:65], off
	s_branch .Lwtd_3

.Lwtd_3:
	s_nop 1
	v_mul_f32_e32 v64, 0xbfb8aa3b, v168
	v_pk_mul_f32 v[70:71], v[50:51], v[64:65] op_sel_hi:[1,0]
	v_pk_mul_f32 v[72:73], v[56:57], v[64:65] op_sel_hi:[1,0]
	v_pk_mul_f32 v[74:75], v[52:53], v[64:65] op_sel_hi:[1,0]
	v_pk_mul_f32 v[64:65], v[54:55], v[64:65] op_sel_hi:[1,0]
	v_exp_f32_e32 v70, v70
	v_exp_f32_e32 v71, v71
	v_exp_f32_e32 v72, v72
	v_exp_f32_e32 v73, v73
	v_exp_f32_e32 v74, v74
	v_exp_f32_e32 v75, v75
	v_exp_f32_e32 v64, v64
	v_exp_f32_e32 v65, v65
	v_pk_add_f32 v[70:71], v[70:71], 1.0 op_sel_hi:[1,0]
	v_pk_add_f32 v[72:73], v[72:73], 1.0 op_sel_hi:[1,0]
	v_pk_add_f32 v[74:75], v[74:75], 1.0 op_sel_hi:[1,0]
	v_pk_add_f32 v[64:65], v[64:65], 1.0 op_sel_hi:[1,0]
	v_rcp_f32_e32 v70, v70
	v_rcp_f32_e32 v71, v71
	v_rcp_f32_e32 v72, v72
	v_rcp_f32_e32 v73, v73
	v_rcp_f32_e32 v74, v74
	v_rcp_f32_e32 v75, v75
	v_rcp_f32_e32 v64, v64
	v_rcp_f32_e32 v65, v65
	s_nop 0
	v_mul_f32_e32 v62, v168, v168
	v_pk_mul_f32 v[54:55], v[54:55], v[66:67]
	v_pk_mul_f32 v[64:65], v[62:63], v[64:65] op_sel_hi:[0,1]
	v_pk_mul_f32 v[54:55], v[54:55], v[64:65]
	v_pk_mul_f32 v[52:53], v[52:53], v[60:61]
	v_pk_mul_f32 v[50:51], v[50:51], v[58:59]
	v_pk_mul_f32 v[58:59], v[62:63], v[70:71] op_sel_hi:[0,1]
	v_pk_mul_f32 v[60:61], v[62:63], v[74:75] op_sel_hi:[0,1]
	v_pk_mul_f32 v[56:57], v[56:57], v[68:69]
	v_pk_mul_f32 v[66:67], v[62:63], v[72:73] op_sel_hi:[0,1]
	v_pk_mul_f32 v[60:61], v[52:53], v[60:61]
	v_pk_mul_f32 v[52:53], v[50:51], v[58:59]
	v_cvt_pk_bf16_f32 v50, v54, v55
	s_mov_b64 s[2:3], 0xb0000
	v_pk_mul_f32 v[56:57], v[56:57], v[66:67]
	v_lshl_add_u64 v[54:55], v[116:117], 0, s[2:3]
	v_cvt_pk_bf16_f32 v51, v56, v57
	v_cvt_pk_bf16_f32 v52, v52, v53
	v_cvt_pk_bf16_f32 v53, v60, v61
	s_cmp_eq_u32 s98, 1
	s_cbranch_scc1 .Lwt_4
	global_store_dwordx4 v[54:55], v[50:53], off
	s_branch .Lwtd_4

.Lwtd_4:
	s_nop 1
	v_mul_f32_e32 v52, 0xbfb8aa3b, v169
	v_pk_mul_f32 v[54:55], v[34:35], v[52:53] op_sel_hi:[1,0]
	v_pk_mul_f32 v[56:57], v[40:41], v[52:53] op_sel_hi:[1,0]
	v_pk_mul_f32 v[58:59], v[36:37], v[52:53] op_sel_hi:[1,0]
	v_pk_mul_f32 v[52:53], v[38:39], v[52:53] op_sel_hi:[1,0]
	v_exp_f32_e32 v54, v54
	v_exp_f32_e32 v55, v55
	v_exp_f32_e32 v56, v56
	v_exp_f32_e32 v57, v57
	v_exp_f32_e32 v58, v58
	v_exp_f32_e32 v59, v59
	v_exp_f32_e32 v52, v52
	v_exp_f32_e32 v53, v53
	v_pk_add_f32 v[54:55], v[54:55], 1.0 op_sel_hi:[1,0]
	v_pk_add_f32 v[56:57], v[56:57], 1.0 op_sel_hi:[1,0]
	v_pk_add_f32 v[58:59], v[58:59], 1.0 op_sel_hi:[1,0]
	v_pk_add_f32 v[52:53], v[52:53], 1.0 op_sel_hi:[1,0]
	v_rcp_f32_e32 v54, v54
	v_rcp_f32_e32 v55, v55
	v_rcp_f32_e32 v56, v56
	v_rcp_f32_e32 v57, v57
	v_rcp_f32_e32 v58, v58
	v_rcp_f32_e32 v59, v59
	v_rcp_f32_e32 v52, v52
	v_rcp_f32_e32 v53, v53
	s_nop 0
	v_mul_f32_e32 v50, v169, v169
	v_pk_mul_f32 v[38:39], v[38:39], v[46:47]
	v_pk_mul_f32 v[46:47], v[50:51], v[52:53] op_sel_hi:[0,1]
	v_pk_mul_f32 v[38:39], v[38:39], v[46:47]
	v_pk_mul_f32 v[36:37], v[36:37], v[44:45]
	v_pk_mul_f32 v[34:35], v[34:35], v[42:43]
	v_pk_mul_f32 v[42:43], v[50:51], v[54:55] op_sel_hi:[0,1]
	v_pk_mul_f32 v[44:45], v[50:51], v[58:59] op_sel_hi:[0,1]
	v_pk_mul_f32 v[40:41], v[40:41], v[48:49]
	v_pk_mul_f32 v[48:49], v[50:51], v[56:57] op_sel_hi:[0,1]
	v_pk_mul_f32 v[44:45], v[36:37], v[44:45]
	v_pk_mul_f32 v[36:37], v[34:35], v[42:43]
	v_cvt_pk_bf16_f32 v34, v38, v39
	s_mov_b64 s[2:3], 0xc6000
	v_pk_mul_f32 v[40:41], v[40:41], v[48:49]
	v_lshl_add_u64 v[38:39], v[116:117], 0, s[2:3]
	v_cvt_pk_bf16_f32 v35, v40, v41
	v_cvt_pk_bf16_f32 v36, v36, v37
	v_cvt_pk_bf16_f32 v37, v44, v45
	s_cmp_eq_u32 s98, 1
	s_cbranch_scc1 .Lwt_5
	global_store_dwordx4 v[38:39], v[34:37], off
	s_branch .Lwtd_5

.Lwtd_5:
	s_nop 1
	v_mul_f32_e32 v36, 0xbfb8aa3b, v149
	v_pk_mul_f32 v[38:39], v[18:19], v[36:37] op_sel_hi:[1,0]
	v_pk_mul_f32 v[40:41], v[24:25], v[36:37] op_sel_hi:[1,0]
	v_pk_mul_f32 v[42:43], v[20:21], v[36:37] op_sel_hi:[1,0]
	v_pk_mul_f32 v[36:37], v[22:23], v[36:37] op_sel_hi:[1,0]
	v_exp_f32_e32 v38, v38
	v_exp_f32_e32 v39, v39
	v_exp_f32_e32 v40, v40
	v_exp_f32_e32 v41, v41
	v_exp_f32_e32 v42, v42
	v_exp_f32_e32 v43, v43
	v_exp_f32_e32 v36, v36
	v_exp_f32_e32 v37, v37
	v_pk_add_f32 v[38:39], v[38:39], 1.0 op_sel_hi:[1,0]
	v_pk_add_f32 v[40:41], v[40:41], 1.0 op_sel_hi:[1,0]
	v_pk_add_f32 v[42:43], v[42:43], 1.0 op_sel_hi:[1,0]
	v_pk_add_f32 v[36:37], v[36:37], 1.0 op_sel_hi:[1,0]
	v_rcp_f32_e32 v38, v38
	v_rcp_f32_e32 v39, v39
	v_rcp_f32_e32 v40, v40
	v_rcp_f32_e32 v41, v41
	v_rcp_f32_e32 v42, v42
	v_rcp_f32_e32 v43, v43
	v_rcp_f32_e32 v36, v36
	v_rcp_f32_e32 v37, v37
	s_nop 0
	v_mul_f32_e32 v34, v149, v149
	v_pk_mul_f32 v[22:23], v[22:23], v[30:31]
	v_pk_mul_f32 v[30:31], v[34:35], v[36:37] op_sel_hi:[0,1]
	v_pk_mul_f32 v[22:23], v[22:23], v[30:31]
	v_pk_mul_f32 v[20:21], v[20:21], v[28:29]
	v_pk_mul_f32 v[18:19], v[18:19], v[26:27]
	v_pk_mul_f32 v[26:27], v[34:35], v[38:39] op_sel_hi:[0,1]
	v_pk_mul_f32 v[28:29], v[34:35], v[42:43] op_sel_hi:[0,1]
	v_pk_mul_f32 v[24:25], v[24:25], v[32:33]
	v_pk_mul_f32 v[32:33], v[34:35], v[40:41] op_sel_hi:[0,1]
	v_pk_mul_f32 v[28:29], v[20:21], v[28:29]
	v_pk_mul_f32 v[20:21], v[18:19], v[26:27]
	v_cvt_pk_bf16_f32 v18, v22, v23
	s_mov_b64 s[2:3], 0xdc000
	v_pk_mul_f32 v[24:25], v[24:25], v[32:33]
	v_lshl_add_u64 v[22:23], v[116:117], 0, s[2:3]
	v_cvt_pk_bf16_f32 v19, v24, v25
	v_cvt_pk_bf16_f32 v20, v20, v21
	v_cvt_pk_bf16_f32 v21, v28, v29
	s_cmp_eq_u32 s98, 1
	s_cbranch_scc1 .Lwt_6
	global_store_dwordx4 v[22:23], v[18:21], off
	s_branch .Lwtd_6

.Lwtd_6:
	s_nop 1
	v_mul_f32_e32 v18, v140, v140
	v_mul_f32_e32 v20, 0xbfb8aa3b, v140
	v_pk_mul_f32 v[22:23], v[2:3], v[20:21] op_sel_hi:[1,0]
	v_pk_mul_f32 v[24:25], v[8:9], v[20:21] op_sel_hi:[1,0]
	v_pk_mul_f32 v[26:27], v[4:5], v[20:21] op_sel_hi:[1,0]
	v_pk_mul_f32 v[20:21], v[6:7], v[20:21] op_sel_hi:[1,0]
	v_exp_f32_e32 v22, v22
	v_exp_f32_e32 v23, v23
	v_exp_f32_e32 v24, v24
	v_exp_f32_e32 v25, v25
	v_exp_f32_e32 v26, v26
	v_exp_f32_e32 v27, v27
	v_exp_f32_e32 v20, v20
	v_exp_f32_e32 v21, v21
	v_pk_add_f32 v[22:23], v[22:23], 1.0 op_sel_hi:[1,0]
	v_pk_add_f32 v[24:25], v[24:25], 1.0 op_sel_hi:[1,0]
	v_pk_add_f32 v[26:27], v[26:27], 1.0 op_sel_hi:[1,0]
	v_pk_add_f32 v[20:21], v[20:21], 1.0 op_sel_hi:[1,0]
	v_rcp_f32_e32 v22, v22
	v_rcp_f32_e32 v23, v23
	v_rcp_f32_e32 v24, v24
	v_rcp_f32_e32 v25, v25
	v_rcp_f32_e32 v26, v26
	v_rcp_f32_e32 v27, v27
	v_rcp_f32_e32 v20, v20
	v_rcp_f32_e32 v21, v21
	s_nop 0
	v_pk_mul_f32 v[6:7], v[6:7], v[14:15]
	v_pk_mul_f32 v[14:15], v[18:19], v[20:21] op_sel_hi:[0,1]
	v_pk_mul_f32 v[6:7], v[6:7], v[14:15]
	v_pk_mul_f32 v[4:5], v[4:5], v[12:13]
	v_pk_mul_f32 v[2:3], v[2:3], v[10:11]
	v_pk_mul_f32 v[10:11], v[18:19], v[22:23] op_sel_hi:[0,1]
	v_pk_mul_f32 v[12:13], v[18:19], v[26:27] op_sel_hi:[0,1]
	v_pk_mul_f32 v[12:13], v[4:5], v[12:13]
	v_pk_mul_f32 v[4:5], v[2:3], v[10:11]
	v_cvt_pk_bf16_f32 v2, v6, v7
	s_mov_b64 s[2:3], 0xf2000
	v_pk_mul_f32 v[8:9], v[8:9], v[16:17]
	v_pk_mul_f32 v[16:17], v[18:19], v[24:25] op_sel_hi:[0,1]
	v_lshl_add_u64 v[6:7], v[116:117], 0, s[2:3]
	v_pk_mul_f32 v[8:9], v[8:9], v[16:17]
	s_nop 0
	v_cvt_pk_bf16_f32 v3, v8, v9
	v_cvt_pk_bf16_f32 v4, v4, v5
	v_cvt_pk_bf16_f32 v5, v12, v13
	s_cmp_eq_u32 s98, 1
	s_cbranch_scc1 .Lwt_7
	global_store_dwordx4 v[6:7], v[2:5], off
	s_branch .Lwtd_7

.LBB0_1725:
	s_add_u32 s4, s50, 0xfffffe00
	s_addc_u32 s5, s51, -1
	s_add_i32 s3, s88, s12
	v_lshl_add_u32 v140, v141, 4, s3
	ds_read_b128 v[152:155], v140
	ds_read_b128 v[156:159], v140 offset:256
	ds_read_b128 v[160:163], v140 offset:512
	ds_read_b128 v[164:167], v140 offset:768
	s_waitcnt lgkmcnt(0)
	s_waitcnt lgkmcnt(0)
	v_mov_b32_e32 v168, v153
	v_mov_b32_e32 v169, v154
	v_mov_b32_e32 v153, v155
	v_pk_add_f32 v[152:153], v[168:169], v[152:153]
	s_lshl_b32 s3, s10, 8
	v_add_f32_e32 v149, v152, v153
	v_mov_b32_e32 v152, v157
	v_mov_b32_e32 v153, v158
	v_mov_b32_e32 v157, v159
	v_fmamk_f32 v149, v149, 0x3a800000, v148
	v_pk_add_f32 v[152:153], v[152:153], v[156:157]
	v_rsq_f32_e32 v170, v149
	v_add_f32_e32 v149, v152, v153
	v_mov_b32_e32 v152, v161
	v_mov_b32_e32 v153, v162
	v_mov_b32_e32 v161, v163
	v_fmamk_f32 v149, v149, 0x3a800000, v148
	v_pk_add_f32 v[152:153], v[152:153], v[160:161]
	v_rsq_f32_e32 v171, v149
	v_add_f32_e32 v149, v152, v153
	v_mov_b32_e32 v152, v165
	v_mov_b32_e32 v153, v166
	v_mov_b32_e32 v165, v167
	v_fmamk_f32 v149, v149, 0x3a800000, v148
	v_pk_add_f32 v[152:153], v[152:153], v[164:165]
	v_rsq_f32_e32 v172, v149
	v_add_f32_e32 v149, v152, v153
	ds_read_b128 v[152:155], v140 offset:2048
	ds_read_b128 v[156:159], v140 offset:2304
	ds_read_b128 v[160:163], v140 offset:2560
	ds_read_b128 v[164:167], v140 offset:2816
	v_fmamk_f32 v149, v149, 0x3a800000, v148
	s_waitcnt lgkmcnt(0)
	v_mov_b32_e32 v168, v153
	v_mov_b32_e32 v169, v154
	v_mov_b32_e32 v153, v155
	v_pk_add_f32 v[152:153], v[168:169], v[152:153]
	v_rsq_f32_e32 v173, v149
	v_add_f32_e32 v140, v152, v153
	v_mov_b32_e32 v152, v157
	v_mov_b32_e32 v153, v158
	v_mov_b32_e32 v157, v159
	v_fmamk_f32 v140, v140, 0x3a800000, v148
	v_pk_add_f32 v[152:153], v[152:153], v[156:157]
	v_rsq_f32_e32 v168, v140
	v_add_f32_e32 v140, v152, v153
	v_mov_b32_e32 v152, v161
	v_mov_b32_e32 v153, v162
	v_mov_b32_e32 v161, v163
	v_fmamk_f32 v140, v140, 0x3a800000, v148
	v_pk_add_f32 v[152:153], v[152:153], v[160:161]
	v_rsq_f32_e32 v169, v140
	v_add_f32_e32 v140, v152, v153
	v_mov_b32_e32 v152, v165
	v_mov_b32_e32 v153, v166
	v_mov_b32_e32 v165, v167
	v_fmamk_f32 v140, v140, 0x3a800000, v148
	v_pk_add_f32 v[152:153], v[152:153], v[164:165]
	v_rsq_f32_e32 v149, v140
	v_add_f32_e32 v140, v152, v153
	v_mul_f32_e32 v153, 0xbfb8aa3b, v170
	v_pk_mul_f32 v[154:155], v[118:119], v[152:153] op_sel:[0,1]
	v_pk_mul_f32 v[156:157], v[114:115], v[152:153] op_sel:[0,1]
	v_pk_mul_f32 v[158:159], v[120:121], v[152:153] op_sel:[0,1]
	v_pk_mul_f32 v[160:161], v[116:117], v[152:153] op_sel:[0,1]
	v_exp_f32_e32 v154, v154
	v_exp_f32_e32 v155, v155
	v_exp_f32_e32 v156, v156
	v_exp_f32_e32 v157, v157
	v_exp_f32_e32 v158, v158
	v_exp_f32_e32 v159, v159
	v_exp_f32_e32 v160, v160
	v_exp_f32_e32 v161, v161
	v_pk_add_f32 v[154:155], v[154:155], 1.0 op_sel_hi:[1,0]
	v_pk_add_f32 v[156:157], v[156:157], 1.0 op_sel_hi:[1,0]
	v_pk_add_f32 v[158:159], v[158:159], 1.0 op_sel_hi:[1,0]
	v_pk_add_f32 v[160:161], v[160:161], 1.0 op_sel_hi:[1,0]
	v_rcp_f32_e32 v154, v154
	v_rcp_f32_e32 v155, v155
	v_rcp_f32_e32 v156, v156
	v_rcp_f32_e32 v157, v157
	v_rcp_f32_e32 v158, v158
	v_rcp_f32_e32 v159, v159
	v_rcp_f32_e32 v160, v160
	v_rcp_f32_e32 v161, v161
	s_nop 0
	s_add_i32 s3, s3, s82
	v_add_u32_e32 v141, s3, v141
	s_lshl_b32 s3, s83, 7
	v_mul_f32_e32 v152, v170, v170
	s_or_b32 s3, s3, s84
	v_pk_mul_f32 v[120:121], v[120:121], v[128:129]
	v_pk_mul_f32 v[118:119], v[118:119], v[126:127]
	v_pk_mul_f32 v[126:127], v[152:153], v[154:155] op_sel_hi:[0,1]
	v_pk_mul_f32 v[128:129], v[152:153], v[158:159] op_sel_hi:[0,1]
	v_pk_mul_f32 v[114:115], v[114:115], v[122:123]
	v_pk_mul_f32 v[122:123], v[152:153], v[156:157] op_sel_hi:[0,1]
	v_readlane_b32 s12, v255, 0
	v_lshl_add_u32 v150, v150, 3, s3
	v_pk_mul_f32 v[120:121], v[120:121], v[128:129]
	v_pk_mul_f32 v[118:119], v[118:119], v[126:127]
	v_pk_mul_f32 v[116:117], v[116:117], v[124:125]
	v_pk_mul_f32 v[124:125], v[152:153], v[160:161] op_sel_hi:[0,1]
	v_pk_mul_f32 v[114:115], v[114:115], v[122:123]
	v_readlane_b32 s13, v255, 1
	s_waitcnt lgkmcnt(0)
	v_ashrrev_i32_e32 v151, 31, v150
	v_pk_mul_f32 v[116:117], v[116:117], v[124:125]
	v_cvt_pk_bf16_f32 v118, v118, v119
	v_cvt_pk_bf16_f32 v119, v120, v121
	v_cvt_pk_bf16_f32 v120, v114, v115
	v_mov_b64_e32 v[114:115], s[12:13]
	v_cvt_pk_bf16_f32 v121, v116, v117
	v_mad_i64_i32 v[122:123], s[12:13], v141, s91, v[114:115]
	v_lshlrev_b64 v[116:117], 1, v[150:151]
	v_lshl_add_u64 v[116:117], v[122:123], 0, v[116:117]
	s_cmp_eq_u32 s98, 1
	s_cbranch_scc1 .Lwt_8
	global_store_dwordx4 v[116:117], v[118:121], off
	s_branch .Lwtd_8

.Lwtd_8:
	v_fmamk_f32 v140, v140, 0x3a800000, v148
	v_rsq_f32_e32 v140, v140
	v_mul_f32_e32 v120, 0xbfb8aa3b, v171
	v_pk_mul_f32 v[122:123], v[98:99], v[120:121] op_sel_hi:[1,0]
	v_pk_mul_f32 v[124:125], v[104:105], v[120:121] op_sel_hi:[1,0]
	v_pk_mul_f32 v[126:127], v[100:101], v[120:121] op_sel_hi:[1,0]
	v_pk_mul_f32 v[120:121], v[102:103], v[120:121] op_sel_hi:[1,0]
	v_exp_f32_e32 v122, v122
	v_exp_f32_e32 v123, v123
	v_exp_f32_e32 v124, v124
	v_exp_f32_e32 v125, v125
	v_exp_f32_e32 v126, v126
	v_exp_f32_e32 v127, v127
	v_exp_f32_e32 v120, v120
	v_exp_f32_e32 v121, v121
	v_pk_add_f32 v[122:123], v[122:123], 1.0 op_sel_hi:[1,0]
	v_pk_add_f32 v[124:125], v[124:125], 1.0 op_sel_hi:[1,0]
	v_pk_add_f32 v[126:127], v[126:127], 1.0 op_sel_hi:[1,0]
	v_pk_add_f32 v[120:121], v[120:121], 1.0 op_sel_hi:[1,0]
	v_rcp_f32_e32 v122, v122
	v_rcp_f32_e32 v123, v123
	v_rcp_f32_e32 v124, v124
	v_rcp_f32_e32 v125, v125
	v_rcp_f32_e32 v126, v126
	v_rcp_f32_e32 v127, v127
	v_rcp_f32_e32 v120, v120
	v_rcp_f32_e32 v121, v121
	s_nop 0
	v_mul_f32_e32 v118, v171, v171
	v_pk_mul_f32 v[102:103], v[102:103], v[110:111]
	v_pk_mul_f32 v[110:111], v[118:119], v[120:121] op_sel_hi:[0,1]
	v_pk_mul_f32 v[102:103], v[102:103], v[110:111]
	v_pk_mul_f32 v[100:101], v[100:101], v[108:109]
	v_pk_mul_f32 v[98:99], v[98:99], v[106:107]
	v_pk_mul_f32 v[106:107], v[118:119], v[122:123] op_sel_hi:[0,1]
	v_pk_mul_f32 v[108:109], v[118:119], v[126:127] op_sel_hi:[0,1]
	v_pk_mul_f32 v[104:105], v[104:105], v[112:113]
	v_pk_mul_f32 v[112:113], v[118:119], v[124:125] op_sel_hi:[0,1]
	v_pk_mul_f32 v[108:109], v[100:101], v[108:109]
	v_pk_mul_f32 v[100:101], v[98:99], v[106:107]
	v_cvt_pk_bf16_f32 v98, v102, v103
	s_mov_b64 s[12:13], 0x16000
	v_pk_mul_f32 v[104:105], v[104:105], v[112:113]
	v_lshl_add_u64 v[102:103], v[116:117], 0, s[12:13]
	v_cvt_pk_bf16_f32 v99, v104, v105
	v_cvt_pk_bf16_f32 v100, v100, v101
	v_cvt_pk_bf16_f32 v101, v108, v109
	s_cmp_eq_u32 s98, 1
	s_cbranch_scc1 .Lwt_9
	global_store_dwordx4 v[102:103], v[98:101], off
	s_branch .Lwtd_9

.Lwtd_9:
	s_andn2_b64 vcc, exec, s[0:1]
	s_nop 0
	v_mul_f32_e32 v100, 0xbfb8aa3b, v172
	v_pk_mul_f32 v[102:103], v[82:83], v[100:101] op_sel_hi:[1,0]
	v_pk_mul_f32 v[104:105], v[88:89], v[100:101] op_sel_hi:[1,0]
	v_pk_mul_f32 v[106:107], v[84:85], v[100:101] op_sel_hi:[1,0]
	v_pk_mul_f32 v[100:101], v[86:87], v[100:101] op_sel_hi:[1,0]
	v_exp_f32_e32 v102, v102
	v_exp_f32_e32 v103, v103
	v_exp_f32_e32 v104, v104
	v_exp_f32_e32 v105, v105
	v_exp_f32_e32 v106, v106
	v_exp_f32_e32 v107, v107
	v_exp_f32_e32 v100, v100
	v_exp_f32_e32 v101, v101
	v_pk_add_f32 v[102:103], v[102:103], 1.0 op_sel_hi:[1,0]
	v_pk_add_f32 v[104:105], v[104:105], 1.0 op_sel_hi:[1,0]
	v_pk_add_f32 v[106:107], v[106:107], 1.0 op_sel_hi:[1,0]
	v_pk_add_f32 v[100:101], v[100:101], 1.0 op_sel_hi:[1,0]
	v_rcp_f32_e32 v102, v102
	v_rcp_f32_e32 v103, v103
	v_rcp_f32_e32 v104, v104
	v_rcp_f32_e32 v105, v105
	v_rcp_f32_e32 v106, v106
	v_rcp_f32_e32 v107, v107
	v_rcp_f32_e32 v100, v100
	v_rcp_f32_e32 v101, v101
	s_nop 0
	v_mul_f32_e32 v98, v172, v172
	v_pk_mul_f32 v[86:87], v[86:87], v[94:95]
	v_pk_mul_f32 v[94:95], v[98:99], v[100:101] op_sel_hi:[0,1]
	v_pk_mul_f32 v[86:87], v[86:87], v[94:95]
	v_pk_mul_f32 v[84:85], v[84:85], v[92:93]
	v_pk_mul_f32 v[82:83], v[82:83], v[90:91]
	v_pk_mul_f32 v[90:91], v[98:99], v[102:103] op_sel_hi:[0,1]
	v_pk_mul_f32 v[92:93], v[98:99], v[106:107] op_sel_hi:[0,1]
	v_pk_mul_f32 v[88:89], v[88:89], v[96:97]
	v_pk_mul_f32 v[96:97], v[98:99], v[104:105] op_sel_hi:[0,1]
	v_pk_mul_f32 v[92:93], v[84:85], v[92:93]
	v_pk_mul_f32 v[84:85], v[82:83], v[90:91]
	v_cvt_pk_bf16_f32 v82, v86, v87
	s_mov_b64 s[12:13], 0x2c000
	v_pk_mul_f32 v[88:89], v[88:89], v[96:97]
	v_lshl_add_u64 v[86:87], v[116:117], 0, s[12:13]
	v_cvt_pk_bf16_f32 v83, v88, v89
	v_cvt_pk_bf16_f32 v84, v84, v85
	v_cvt_pk_bf16_f32 v85, v92, v93
	s_cmp_eq_u32 s98, 1
	s_cbranch_scc1 .Lwt_10
	global_store_dwordx4 v[86:87], v[82:85], off
	s_branch .Lwtd_10

.Lwtd_10:
	s_nop 1
	v_mul_f32_e32 v84, 0xbfb8aa3b, v173
	v_pk_mul_f32 v[86:87], v[62:63], v[84:85] op_sel_hi:[1,0]
	v_pk_mul_f32 v[88:89], v[72:73], v[84:85] op_sel_hi:[1,0]
	v_pk_mul_f32 v[90:91], v[64:65], v[84:85] op_sel_hi:[1,0]
	v_pk_mul_f32 v[84:85], v[70:71], v[84:85] op_sel_hi:[1,0]
	v_exp_f32_e32 v86, v86
	v_exp_f32_e32 v87, v87
	v_exp_f32_e32 v88, v88
	v_exp_f32_e32 v89, v89
	v_exp_f32_e32 v90, v90
	v_exp_f32_e32 v91, v91
	v_exp_f32_e32 v84, v84
	v_exp_f32_e32 v85, v85
	v_pk_add_f32 v[86:87], v[86:87], 1.0 op_sel_hi:[1,0]
	v_pk_add_f32 v[88:89], v[88:89], 1.0 op_sel_hi:[1,0]
	v_pk_add_f32 v[90:91], v[90:91], 1.0 op_sel_hi:[1,0]
	v_pk_add_f32 v[84:85], v[84:85], 1.0 op_sel_hi:[1,0]
	v_rcp_f32_e32 v86, v86
	v_rcp_f32_e32 v87, v87
	v_rcp_f32_e32 v88, v88
	v_rcp_f32_e32 v89, v89
	v_rcp_f32_e32 v90, v90
	v_rcp_f32_e32 v91, v91
	v_rcp_f32_e32 v84, v84
	v_rcp_f32_e32 v85, v85
	s_nop 0
	v_mul_f32_e32 v82, v173, v173
	v_pk_mul_f32 v[70:71], v[70:71], v[78:79]
	v_pk_mul_f32 v[78:79], v[82:83], v[84:85] op_sel_hi:[0,1]
	v_pk_mul_f32 v[70:71], v[70:71], v[78:79]
	v_pk_mul_f32 v[64:65], v[64:65], v[76:77]
	v_pk_mul_f32 v[62:63], v[62:63], v[74:75]
	v_pk_mul_f32 v[74:75], v[82:83], v[86:87] op_sel_hi:[0,1]
	v_pk_mul_f32 v[76:77], v[82:83], v[90:91] op_sel_hi:[0,1]
	v_pk_mul_f32 v[72:73], v[72:73], v[80:81]
	v_pk_mul_f32 v[80:81], v[82:83], v[88:89] op_sel_hi:[0,1]
	v_pk_mul_f32 v[76:77], v[64:65], v[76:77]
	v_pk_mul_f32 v[64:65], v[62:63], v[74:75]
	v_cvt_pk_bf16_f32 v62, v70, v71
	s_mov_b64 s[12:13], 0x42000
	v_pk_mul_f32 v[72:73], v[72:73], v[80:81]
	v_lshl_add_u64 v[70:71], v[116:117], 0, s[12:13]
	v_cvt_pk_bf16_f32 v63, v72, v73
	v_cvt_pk_bf16_f32 v64, v64, v65
	v_cvt_pk_bf16_f32 v65, v76, v77
	s_cmp_eq_u32 s98, 1
	s_cbranch_scc1 .Lwt_11
	global_store_dwordx4 v[70:71], v[62:65], off
	s_branch .Lwtd_11

.Lwtd_11:
	s_nop 1
	v_mul_f32_e32 v64, 0xbfb8aa3b, v168
	v_pk_mul_f32 v[70:71], v[50:51], v[64:65] op_sel_hi:[1,0]
	v_pk_mul_f32 v[72:73], v[56:57], v[64:65] op_sel_hi:[1,0]
	v_pk_mul_f32 v[74:75], v[52:53], v[64:65] op_sel_hi:[1,0]
	v_pk_mul_f32 v[64:65], v[54:55], v[64:65] op_sel_hi:[1,0]
	v_exp_f32_e32 v70, v70
	v_exp_f32_e32 v71, v71
	v_exp_f32_e32 v72, v72
	v_exp_f32_e32 v73, v73
	v_exp_f32_e32 v74, v74
	v_exp_f32_e32 v75, v75
	v_exp_f32_e32 v64, v64
	v_exp_f32_e32 v65, v65
	v_pk_add_f32 v[70:71], v[70:71], 1.0 op_sel_hi:[1,0]
	v_pk_add_f32 v[72:73], v[72:73], 1.0 op_sel_hi:[1,0]
	v_pk_add_f32 v[74:75], v[74:75], 1.0 op_sel_hi:[1,0]
	v_pk_add_f32 v[64:65], v[64:65], 1.0 op_sel_hi:[1,0]
	v_rcp_f32_e32 v70, v70
	v_rcp_f32_e32 v71, v71
	v_rcp_f32_e32 v72, v72
	v_rcp_f32_e32 v73, v73
	v_rcp_f32_e32 v74, v74
	v_rcp_f32_e32 v75, v75
	v_rcp_f32_e32 v64, v64
	v_rcp_f32_e32 v65, v65
	s_nop 0
	v_mul_f32_e32 v62, v168, v168
	v_pk_mul_f32 v[54:55], v[54:55], v[66:67]
	v_pk_mul_f32 v[64:65], v[62:63], v[64:65] op_sel_hi:[0,1]
	v_pk_mul_f32 v[54:55], v[54:55], v[64:65]
	v_pk_mul_f32 v[52:53], v[52:53], v[60:61]
	v_pk_mul_f32 v[50:51], v[50:51], v[58:59]
	v_pk_mul_f32 v[58:59], v[62:63], v[70:71] op_sel_hi:[0,1]
	v_pk_mul_f32 v[60:61], v[62:63], v[74:75] op_sel_hi:[0,1]
	v_pk_mul_f32 v[56:57], v[56:57], v[68:69]
	v_pk_mul_f32 v[66:67], v[62:63], v[72:73] op_sel_hi:[0,1]
	v_pk_mul_f32 v[60:61], v[52:53], v[60:61]
	v_pk_mul_f32 v[52:53], v[50:51], v[58:59]
	v_cvt_pk_bf16_f32 v50, v54, v55
	s_mov_b64 s[12:13], 0xb0000
	v_pk_mul_f32 v[56:57], v[56:57], v[66:67]
	v_lshl_add_u64 v[54:55], v[116:117], 0, s[12:13]
	v_cvt_pk_bf16_f32 v51, v56, v57
	v_cvt_pk_bf16_f32 v52, v52, v53
	v_cvt_pk_bf16_f32 v53, v60, v61
	s_cmp_eq_u32 s98, 1
	s_cbranch_scc1 .Lwt_12
	global_store_dwordx4 v[54:55], v[50:53], off
	s_branch .Lwtd_12

.Lwtd_12:
	s_nop 1
	v_mul_f32_e32 v52, 0xbfb8aa3b, v169
	v_pk_mul_f32 v[54:55], v[34:35], v[52:53] op_sel_hi:[1,0]
	v_pk_mul_f32 v[56:57], v[40:41], v[52:53] op_sel_hi:[1,0]
	v_pk_mul_f32 v[58:59], v[36:37], v[52:53] op_sel_hi:[1,0]
	v_pk_mul_f32 v[52:53], v[38:39], v[52:53] op_sel_hi:[1,0]
	v_exp_f32_e32 v54, v54
	v_exp_f32_e32 v55, v55
	v_exp_f32_e32 v56, v56
	v_exp_f32_e32 v57, v57
	v_exp_f32_e32 v58, v58
	v_exp_f32_e32 v59, v59
	v_exp_f32_e32 v52, v52
	v_exp_f32_e32 v53, v53
	v_pk_add_f32 v[54:55], v[54:55], 1.0 op_sel_hi:[1,0]
	v_pk_add_f32 v[56:57], v[56:57], 1.0 op_sel_hi:[1,0]
	v_pk_add_f32 v[58:59], v[58:59], 1.0 op_sel_hi:[1,0]
	v_pk_add_f32 v[52:53], v[52:53], 1.0 op_sel_hi:[1,0]
	v_rcp_f32_e32 v54, v54
	v_rcp_f32_e32 v55, v55
	v_rcp_f32_e32 v56, v56
	v_rcp_f32_e32 v57, v57
	v_rcp_f32_e32 v58, v58
	v_rcp_f32_e32 v59, v59
	v_rcp_f32_e32 v52, v52
	v_rcp_f32_e32 v53, v53
	s_nop 0
	v_mul_f32_e32 v50, v169, v169
	v_pk_mul_f32 v[38:39], v[38:39], v[46:47]
	v_pk_mul_f32 v[46:47], v[50:51], v[52:53] op_sel_hi:[0,1]
	v_pk_mul_f32 v[38:39], v[38:39], v[46:47]
	v_pk_mul_f32 v[36:37], v[36:37], v[44:45]
	v_pk_mul_f32 v[34:35], v[34:35], v[42:43]
	v_pk_mul_f32 v[42:43], v[50:51], v[54:55] op_sel_hi:[0,1]
	v_pk_mul_f32 v[44:45], v[50:51], v[58:59] op_sel_hi:[0,1]
	v_pk_mul_f32 v[40:41], v[40:41], v[48:49]
	v_pk_mul_f32 v[48:49], v[50:51], v[56:57] op_sel_hi:[0,1]
	v_pk_mul_f32 v[44:45], v[36:37], v[44:45]
	v_pk_mul_f32 v[36:37], v[34:35], v[42:43]
	v_cvt_pk_bf16_f32 v34, v38, v39
	s_mov_b64 s[12:13], 0xc6000
	v_pk_mul_f32 v[40:41], v[40:41], v[48:49]
	v_lshl_add_u64 v[38:39], v[116:117], 0, s[12:13]
	v_cvt_pk_bf16_f32 v35, v40, v41
	v_cvt_pk_bf16_f32 v36, v36, v37
	v_cvt_pk_bf16_f32 v37, v44, v45
	s_cmp_eq_u32 s98, 1
	s_cbranch_scc1 .Lwt_13
	global_store_dwordx4 v[38:39], v[34:37], off
	s_branch .Lwtd_13

.Lwtd_13:
	s_nop 1
	v_mul_f32_e32 v36, 0xbfb8aa3b, v149
	v_pk_mul_f32 v[38:39], v[18:19], v[36:37] op_sel_hi:[1,0]
	v_pk_mul_f32 v[40:41], v[24:25], v[36:37] op_sel_hi:[1,0]
	v_pk_mul_f32 v[42:43], v[20:21], v[36:37] op_sel_hi:[1,0]
	v_pk_mul_f32 v[36:37], v[22:23], v[36:37] op_sel_hi:[1,0]
	v_exp_f32_e32 v38, v38
	v_exp_f32_e32 v39, v39
	v_exp_f32_e32 v40, v40
	v_exp_f32_e32 v41, v41
	v_exp_f32_e32 v42, v42
	v_exp_f32_e32 v43, v43
	v_exp_f32_e32 v36, v36
	v_exp_f32_e32 v37, v37
	v_pk_add_f32 v[38:39], v[38:39], 1.0 op_sel_hi:[1,0]
	v_pk_add_f32 v[40:41], v[40:41], 1.0 op_sel_hi:[1,0]
	v_pk_add_f32 v[42:43], v[42:43], 1.0 op_sel_hi:[1,0]
	v_pk_add_f32 v[36:37], v[36:37], 1.0 op_sel_hi:[1,0]
	v_rcp_f32_e32 v38, v38
	v_rcp_f32_e32 v39, v39
	v_rcp_f32_e32 v40, v40
	v_rcp_f32_e32 v41, v41
	v_rcp_f32_e32 v42, v42
	v_rcp_f32_e32 v43, v43
	v_rcp_f32_e32 v36, v36
	v_rcp_f32_e32 v37, v37
	s_nop 0
	v_mul_f32_e32 v34, v149, v149
	v_pk_mul_f32 v[22:23], v[22:23], v[30:31]
	v_pk_mul_f32 v[30:31], v[34:35], v[36:37] op_sel_hi:[0,1]
	v_pk_mul_f32 v[22:23], v[22:23], v[30:31]
	v_pk_mul_f32 v[20:21], v[20:21], v[28:29]
	v_pk_mul_f32 v[18:19], v[18:19], v[26:27]
	v_pk_mul_f32 v[26:27], v[34:35], v[38:39] op_sel_hi:[0,1]
	v_pk_mul_f32 v[28:29], v[34:35], v[42:43] op_sel_hi:[0,1]
	v_pk_mul_f32 v[24:25], v[24:25], v[32:33]
	v_pk_mul_f32 v[32:33], v[34:35], v[40:41] op_sel_hi:[0,1]
	v_pk_mul_f32 v[28:29], v[20:21], v[28:29]
	v_pk_mul_f32 v[20:21], v[18:19], v[26:27]
	v_cvt_pk_bf16_f32 v18, v22, v23
	s_mov_b64 s[12:13], 0xdc000
	v_pk_mul_f32 v[24:25], v[24:25], v[32:33]
	v_lshl_add_u64 v[22:23], v[116:117], 0, s[12:13]
	v_cvt_pk_bf16_f32 v19, v24, v25
	v_cvt_pk_bf16_f32 v20, v20, v21
	v_cvt_pk_bf16_f32 v21, v28, v29
	s_cmp_eq_u32 s98, 1
	s_cbranch_scc1 .Lwt_14
	global_store_dwordx4 v[22:23], v[18:21], off
	s_branch .Lwtd_14

.Lwtd_14:
	s_nop 1
	v_mul_f32_e32 v18, v140, v140
	v_mul_f32_e32 v20, 0xbfb8aa3b, v140
	v_pk_mul_f32 v[22:23], v[2:3], v[20:21] op_sel_hi:[1,0]
	v_pk_mul_f32 v[24:25], v[8:9], v[20:21] op_sel_hi:[1,0]
	v_pk_mul_f32 v[26:27], v[4:5], v[20:21] op_sel_hi:[1,0]
	v_pk_mul_f32 v[20:21], v[6:7], v[20:21] op_sel_hi:[1,0]
	v_exp_f32_e32 v22, v22
	v_exp_f32_e32 v23, v23
	v_exp_f32_e32 v24, v24
	v_exp_f32_e32 v25, v25
	v_exp_f32_e32 v26, v26
	v_exp_f32_e32 v27, v27
	v_exp_f32_e32 v20, v20
	v_exp_f32_e32 v21, v21
	v_pk_add_f32 v[22:23], v[22:23], 1.0 op_sel_hi:[1,0]
	v_pk_add_f32 v[24:25], v[24:25], 1.0 op_sel_hi:[1,0]
	v_pk_add_f32 v[26:27], v[26:27], 1.0 op_sel_hi:[1,0]
	v_pk_add_f32 v[20:21], v[20:21], 1.0 op_sel_hi:[1,0]
	v_rcp_f32_e32 v22, v22
	v_rcp_f32_e32 v23, v23
	v_rcp_f32_e32 v24, v24
	v_rcp_f32_e32 v25, v25
	v_rcp_f32_e32 v26, v26
	v_rcp_f32_e32 v27, v27
	v_rcp_f32_e32 v20, v20
	v_rcp_f32_e32 v21, v21
	s_nop 0
	v_pk_mul_f32 v[6:7], v[6:7], v[14:15]
	v_pk_mul_f32 v[14:15], v[18:19], v[20:21] op_sel_hi:[0,1]
	v_pk_mul_f32 v[6:7], v[6:7], v[14:15]
	v_pk_mul_f32 v[4:5], v[4:5], v[12:13]
	v_pk_mul_f32 v[2:3], v[2:3], v[10:11]
	v_pk_mul_f32 v[10:11], v[18:19], v[22:23] op_sel_hi:[0,1]
	v_pk_mul_f32 v[12:13], v[18:19], v[26:27] op_sel_hi:[0,1]
	v_pk_mul_f32 v[12:13], v[4:5], v[12:13]
	v_pk_mul_f32 v[4:5], v[2:3], v[10:11]
	v_cvt_pk_bf16_f32 v2, v6, v7
	s_mov_b64 s[12:13], 0xf2000
	v_pk_mul_f32 v[8:9], v[8:9], v[16:17]
	v_pk_mul_f32 v[16:17], v[18:19], v[24:25] op_sel_hi:[0,1]
	v_lshl_add_u64 v[6:7], v[116:117], 0, s[12:13]
	v_pk_mul_f32 v[8:9], v[8:9], v[16:17]
	s_nop 0
	v_cvt_pk_bf16_f32 v3, v8, v9
	v_cvt_pk_bf16_f32 v4, v4, v5
	v_cvt_pk_bf16_f32 v5, v12, v13
	s_cmp_eq_u32 s98, 1
	s_cbranch_scc1 .Lwt_15
	global_store_dwordx4 v[6:7], v[2:5], off
	s_branch .Lwtd_15
